# GLA final pass prefetch: K, Q, V row loads with scalar bases
# baseline (speedup 1.0000x reference)
.LBB0_183:
	v_mov_b32_e32 v3, v204
	v_mov_b32_e32 v0, s59
	ds_read_b64 v[28:29], v0
	s_and_b32 s9, s23, 3
	v_mov_b32_e32 v0, s45
	v_ashrrev_i32_e32 v37, 3, v3
	ds_read2_b64 v[24:27], v0 offset1:1
	s_waitcnt lgkmcnt(0)
	v_readfirstlane_b32 s29, v28
	v_readfirstlane_b32 s28, v29
	s_add_u32 s6, s29, 0xe000000
	s_addc_u32 s7, s28, 0
	v_add_u32_e32 v0, s10, v37
	v_mov_b64_e32 v[28:29], s[6:7]
	v_mad_i64_i32 v[30:31], s[36:37], v0, s94, v[28:29]
	v_lshlrev_b32_e32 v0, 3, v3
	v_and_b32_e32 v0, 56, v0
	v_lshl_add_u64 v[30:31], v[30:31], 0, v[0:1]
	v_add_co_u32_e32 v30, vcc, s91, v30
	v_add_u32_e32 v33, 0x400, v3
	s_nop 0
	v_addc_co_u32_e32 v31, vcc, 0, v31, vcc
	global_load_dwordx2 v[64:65], v[30:31], off offset:512
	v_add_u32_e32 v30, 0x200, v3
	v_add_u32_e32 v34, 0x600, v3
	v_ashrrev_i32_e32 v0, 6, v3
	v_lshrrev_b32_e32 v31, 6, v30
	v_ashrrev_i32_e32 v30, 6, v30
	v_ashrrev_i32_e32 v33, 6, v33
	v_lshrrev_b32_e32 v35, 6, v34
	v_ashrrev_i32_e32 v34, 6, v34
	v_and_b32_e32 v0, -16, v0
	v_and_b32_e32 v30, -16, v30
	v_and_b32_e32 v33, -16, v33
	v_and_b32_e32 v34, -16, v34
	v_bfe_u32 v32, v3, 6, 4
	v_add_u32_e32 v0, s21, v0
	v_add_u32_e32 v30, s21, v30
	v_add_u32_e32 v33, s21, v33
	v_add_u32_e32 v34, s21, v34
	v_readfirstlane_b32 s36, v24
	v_or_b32_e32 v24, v0, v32
	v_and_or_b32 v30, v31, 15, v30
	v_or_b32_e32 v32, v33, v32
	v_and_or_b32 v34, v35, 15, v34
	v_readfirstlane_b32 s37, v25
	v_ashrrev_i32_e32 v25, 31, v24
	v_ashrrev_i32_e32 v31, 31, v30
	v_ashrrev_i32_e32 v33, 31, v32
	v_ashrrev_i32_e32 v35, 31, v34
	v_lshlrev_b64 v[24:25], 10, v[24:25]
	v_lshlrev_b64 v[30:31], 10, v[30:31]
	v_lshlrev_b64 v[32:33], 10, v[32:33]
	v_lshlrev_b64 v[34:35], 10, v[34:35]
	v_and_b32_e32 v36, 63, v3
	s_lshl_b32 s35, s9, 6
	v_lshl_add_u64 v[24:25], s[36:37], 0, v[24:25]
	s_lshl_b32 s78, s9, 8
	v_lshl_add_u64 v[30:31], s[36:37], 0, v[30:31]
	v_lshl_add_u64 v[32:33], s[36:37], 0, v[32:33]
	v_lshl_add_u64 v[34:35], s[36:37], 0, v[34:35]
	v_lshl_add_u64 v[24:25], v[24:25], 0, s[78:79]
	v_lshlrev_b32_e32 v0, 2, v36
	v_lshl_add_u64 v[30:31], v[30:31], 0, s[78:79]
	v_lshl_add_u64 v[32:33], v[32:33], 0, s[78:79]
	v_lshl_add_u64 v[34:35], v[34:35], 0, s[78:79]
	v_readfirstlane_b32 s36, v3
	s_or_b32 s35, s35, s84
	v_lshl_add_u64 v[24:25], v[24:25], 0, v[0:1]
	v_lshl_add_u64 v[30:31], v[30:31], 0, v[0:1]
	v_lshl_add_u64 v[32:33], v[32:33], 0, v[0:1]
	v_lshl_add_u64 v[34:35], v[34:35], 0, v[0:1]
	v_or_b32_e32 v0, s35, v36
	s_ashr_i32 s35, s36, 3
	s_and_b32 s35, s35, -8
	v_readfirstlane_b32 s37, v27
	v_readfirstlane_b32 s38, v26
	s_add_i32 s35, s35, s10
	s_lshl_b32 s36, s9, 7
	global_load_dword v96, v[24:25], off
	global_load_dword v95, v[30:31], off
	global_load_dword v94, v[32:33], off
	global_load_dword v93, v[34:35], off
	v_mov_b32_e32 v24, s38
	v_mov_b32_e32 v25, s37
	s_add_u32 s6, s6, s36
	v_lshl_add_u64 v[24:25], v[0:1], 2, v[24:25]
	s_addc_u32 s7, s7, 0
	v_lshlrev_b32_e32 v0, 1, v36
	global_load_dword v97, v[24:25], off
	global_load_dword v92, v[24:25], off offset:1024
	s_mul_i32 s38, s35, 0x1400
	s_add_u32 s36, s6, s38
	s_addc_u32 s37, s7, 0
	s_sub_i32 s38, s35, s10
	s_and_b32 s38, s38, -16
	s_add_i32 s38, s38, s10
	s_mul_i32 s38, s38, 0x1400
	s_lshl_b32 s35, s9, 7
	s_add_u32 s6, s6, s35
	s_addc_u32 s7, s7, 0
	s_add_u32 s6, s6, s38
	s_addc_u32 s7, s7, 0
	global_load_ushort v105, v0, s[36:37] offset:512
	global_load_ushort v101, v0, s[36:37]
	s_add_u32 s36, s36, 0x1400
	s_addc_u32 s37, s37, 0
	global_load_ushort v104, v0, s[36:37] offset:512
	global_load_ushort v100, v0, s[36:37]
	s_add_u32 s36, s36, 0x1400
	s_addc_u32 s37, s37, 0
	global_load_ushort v103, v0, s[36:37] offset:512
	global_load_ushort v99, v0, s[36:37]
	s_add_u32 s36, s36, 0x1400
	s_addc_u32 s37, s37, 0
	global_load_ushort v102, v0, s[36:37] offset:512
	global_load_ushort v98, v0, s[36:37]
	s_add_u32 s36, s36, 0x1400
	s_addc_u32 s37, s37, 0
	global_load_ushort v113, v0, s[36:37] offset:512
	global_load_ushort v109, v0, s[36:37]
	s_add_u32 s36, s36, 0x1400
	s_addc_u32 s37, s37, 0
	global_load_ushort v112, v0, s[36:37] offset:512
	global_load_ushort v108, v0, s[36:37]
	s_add_u32 s36, s36, 0x1400
	s_addc_u32 s37, s37, 0
	global_load_ushort v111, v0, s[36:37] offset:512
	global_load_ushort v107, v0, s[36:37]
	s_add_u32 s36, s36, 0x1400
	s_addc_u32 s37, s37, 0
	global_load_ushort v110, v0, s[36:37] offset:512
	global_load_ushort v106, v0, s[36:37]
	v_and_b32_e32 v0, 0x7f, v3
	v_lshlrev_b32_e32 v0, 1, v0
	global_load_ushort v114, v0, s[6:7] offset:1024
	s_add_u32 s6, s6, 0x1400
	s_addc_u32 s7, s7, 0
	global_load_ushort v183, v0, s[6:7] offset:1024
	s_add_u32 s6, s6, 0x1400
	s_addc_u32 s7, s7, 0
	global_load_ushort v184, v0, s[6:7] offset:1024
	s_add_u32 s6, s6, 0x1400
	s_addc_u32 s7, s7, 0
	global_load_ushort v185, v0, s[6:7] offset:1024
	s_add_u32 s6, s6, 0x1400
	s_addc_u32 s7, s7, 0
	global_load_ushort v186, v0, s[6:7] offset:1024
	s_add_u32 s6, s6, 0x1400
	s_addc_u32 s7, s7, 0
	global_load_ushort v187, v0, s[6:7] offset:1024
	s_add_u32 s6, s6, 0x1400
	s_addc_u32 s7, s7, 0
	global_load_ushort v188, v0, s[6:7] offset:1024
	s_add_u32 s6, s6, 0x1400
	s_addc_u32 s7, s7, 0
	global_load_ushort v115, v0, s[6:7] offset:1024
	s_add_u32 s6, s6, 0x1400
	s_addc_u32 s7, s7, 0
	global_load_ushort v117, v0, s[6:7] offset:1024
	s_add_u32 s6, s6, 0x1400
	s_addc_u32 s7, s7, 0
	global_load_ushort v189, v0, s[6:7] offset:1024
	s_add_u32 s6, s6, 0x1400
	s_addc_u32 s7, s7, 0
	global_load_ushort v190, v0, s[6:7] offset:1024
	s_add_u32 s6, s6, 0x1400
	s_addc_u32 s7, s7, 0
	global_load_ushort v191, v0, s[6:7] offset:1024
	s_add_u32 s6, s6, 0x1400
	s_addc_u32 s7, s7, 0
	global_load_ushort v192, v0, s[6:7] offset:1024
	s_add_u32 s6, s6, 0x1400
	s_addc_u32 s7, s7, 0
	global_load_ushort v193, v0, s[6:7] offset:1024
	s_add_u32 s6, s6, 0x1400
	s_addc_u32 s7, s7, 0
	global_load_ushort v194, v0, s[6:7] offset:1024
	s_add_u32 s6, s6, 0x1400
	s_addc_u32 s7, s7, 0
	global_load_ushort v116, v0, s[6:7] offset:1024
	s_lshl_b32 s6, s26, 3
	s_lshl_b32 s7, s9, 1
	s_or_b32 s6, s6, s7
	s_mul_hi_i32 s7, s6, 0x44
	s_mulk_i32 s6, 0x44
	s_ashr_i32 s26, s27, 31
	s_add_u32 s6, s6, s27
	s_addc_u32 s7, s7, s26
	s_lshl_b64 s[6:7], s[6:7], 14
	s_add_u32 s6, s29, s6
	s_addc_u32 s7, s28, s7
	s_ashr_i32 s11, s11, 2
	v_bfe_u32 v42, v2, 4, 2
	v_and_b32_e32 v43, 15, v2
	v_bfi_b32 v2, -16, s11, v2
	v_ashrrev_i32_e32 v3, 31, v2
	v_lshlrev_b64 v[2:3], 7, v[2:3]
	v_lshl_add_u64 v[2:3], s[6:7], 0, v[2:3]
	v_lshlrev_b32_e32 v40, 4, v42
	v_mov_b32_e32 v41, v1
	v_lshl_add_u64 v[2:3], v[2:3], 0, v[40:41]
	s_mov_b64 s[6:7], 0x18c00000
	v_lshl_add_u64 v[28:29], v[2:3], 0, s[6:7]
	s_mov_b32 s6, 0x18c00000
	v_add_co_u32_e32 v24, vcc, s6, v2
	s_mov_b64 s[6:7], 0x18d10000
	s_nop 0
	v_addc_co_u32_e32 v25, vcc, 0, v3, vcc
	v_lshl_add_u64 v[36:37], v[2:3], 0, s[6:7]
	s_mov_b32 s6, 0x18d10000
	v_add_co_u32_e32 v2, vcc, s6, v2
	s_and_b32 s26, s11, -16
	s_nop 0
	v_addc_co_u32_e32 v3, vcc, 0, v3, vcc
	global_load_dwordx4 v[24:27], v[24:25], off
	s_nop 0
	global_load_dwordx4 v[28:31], v[28:29], off offset:64
	s_nop 0
	global_load_dwordx4 v[32:35], v[2:3], off
	s_nop 0
	global_load_dwordx4 v[36:39], v[36:37], off offset:64
	v_add_u32_e32 v76, s10, v43
	v_mov_b64_e32 v[2:3], s[4:5]
	v_lshlrev_b32_e32 v0, 3, v42
	s_ashr_i32 s27, s26, 31
	v_mad_i64_i32 v[42:43], s[4:5], v76, s94, v[2:3]
	v_lshl_add_u64 v[42:43], v[42:43], 0, s[78:79]
	s_lshl_b64 s[4:5], s[26:27], 1
	v_add_u32_e32 v70, 16, v76
	v_lshl_add_u64 v[42:43], v[42:43], 0, s[4:5]
	v_mad_i64_i32 v[70:71], s[6:7], v70, s94, v[2:3]
	v_lshl_add_u64 v[42:43], v[42:43], 0, v[0:1]
	s_mov_b32 s10, 0xe000000
	v_lshl_add_u64 v[70:71], v[70:71], 0, s[78:79]
	v_add_co_u32_e32 v42, vcc, s10, v42
	v_lshl_add_u64 v[70:71], v[70:71], 0, s[4:5]
	s_nop 0
	v_addc_co_u32_e32 v43, vcc, 0, v43, vcc
	v_lshl_add_u64 v[70:71], v[70:71], 0, v[0:1]
	v_add_co_u32_e32 v72, vcc, s10, v70
	v_add_u32_e32 v70, 32, v76
	s_nop 0
	v_addc_co_u32_e32 v73, vcc, 0, v71, vcc
	v_mad_i64_i32 v[70:71], s[6:7], v70, s94, v[2:3]
	v_lshl_add_u64 v[70:71], v[70:71], 0, s[78:79]
	v_lshl_add_u64 v[70:71], v[70:71], 0, s[4:5]
	v_lshl_add_u64 v[70:71], v[70:71], 0, v[0:1]
	v_add_co_u32_e32 v74, vcc, s10, v70
	v_add_u32_e32 v70, 48, v76
	v_mad_i64_i32 v[2:3], s[6:7], v70, s94, v[2:3]
	v_lshl_add_u64 v[2:3], v[2:3], 0, s[78:79]
	v_lshl_add_u64 v[2:3], v[2:3], 0, s[4:5]
	v_readlane_b32 s4, v245, 46
	v_lshl_add_u64 v[2:3], v[2:3], 0, v[0:1]
	v_addc_co_u32_e32 v75, vcc, 0, v71, vcc
	v_mov_b32_e32 v0, s4
	ds_read_b64 v[118:119], v0
	s_lshl_b64 s[4:5], s[84:85], 2
	v_add_co_u32_e32 v2, vcc, s10, v2
	s_waitcnt lgkmcnt(0)
	v_readfirstlane_b32 s7, v118
	v_readfirstlane_b32 s6, v119
	s_add_u32 s4, s7, s4
	s_addc_u32 s5, s6, s5
	s_lshl_b32 s6, s9, 9
	s_add_u32 s6, s4, s6
	s_addc_u32 s7, s5, 0
	s_lshl_b64 s[4:5], s[26:27], 2
	s_add_u32 s4, s6, s4
	v_addc_co_u32_e32 v3, vcc, 0, v3, vcc
	global_load_dwordx2 v[70:71], v[42:43], off offset:2048
	s_nop 0
	global_load_dwordx2 v[72:73], v[72:73], off offset:2048
	s_nop 0
	global_load_dwordx2 v[74:75], v[74:75], off offset:2048
	s_nop 0
	global_load_dwordx2 v[76:77], v[2:3], off offset:2048
	s_addc_u32 s5, s7, s5
	v_lshl_add_u64 v[2:3], s[4:5], 0, v[40:41]
	global_load_dwordx4 v[40:43], v[2:3], off
